# speedup vs baseline: 1.0437x; 1.0051x over previous
; __device__ __forceinline__ void xcd_share(int ntiles, int& start, int& j, int& per, int& cnt) {
;   const int G = gridDim.x, b = blockIdx.x;
;   if ((G & 7) == 0) {
;     int xcd = b & 7;
;     j = b >> 3;
;     per = G >> 3;
;     int q = ntiles >> 3, r = ntiles & 7;
;     start = xcd < r ? xcd * (q + 1) : r * (q + 1) + (xcd - r) * q;
;     cnt = q + (xcd < r ? 1 : 0);
;   } else {
;     start = 0;
;     cnt = ntiles;
;     j = b;
;     per = G;
;   }
; }
; template <int EPI> ...
;   int startA, jA, perA, cntA;
;   xcd_share(nM * nN, startA, jA, perA, cntA);
;   const int nA = jA < cntA ? (cntA - jA + perA - 1) / perA : 0;
.LBB0_400:
	v_readlane_b32 s0, v255, 9
	v_readlane_b32 s6, v255, 8
	v_readlane_b32 s7, v255, 7
	s_nop 1
	s_mul_i32 s0, s0, s6
	s_add_i32 s0, s0, s7
	s_cmp_ge_i32 s0, s2
	s_cbranch_scc0 .LBB0_382
